# G1: ph_pre step-2 gate loads (ab x4, dt_bias x2, a_log x2) hoisted to the item top beside the conv-weight loads
# baseline (speedup 1.0000x reference)
.LBB0_191:
	s_mul_hi_i32 s0, s28, 0x2aaaaaab
	s_lshr_b32 s1, s0, 31
	s_ashr_i32 s0, s0, 1
	s_add_i32 s1, s0, s1
	v_mbcnt_lo_u32_b32 v216, -1, 0
	v_mbcnt_hi_u32_b32 v216, -1, v216
	s_mul_i32 s0, s1, -12
	v_and_b32_e32 v128, 7, v216
	s_add_i32 s2, s0, s28
	v_lshlrev_b32_e32 v215, 4, v128
	v_lshl_or_b32 v48, s2, 7, v215
	v_add_u32_e32 v0, 0x600, v48
	v_add_u32_e32 v48, 0xc00, v48
	v_ashrrev_i32_e32 v1, 31, v0
	v_ashrrev_i32_e32 v49, 31, v48
	v_lshlrev_b64 v[0:1], 2, v[0:1]
	v_lshlrev_b64 v[48:49], 2, v[48:49]
	v_lshl_add_u64 v[4:5], s[34:35], 0, v[0:1]
	v_lshl_add_u64 v[6:7], s[56:57], 0, v[0:1]
	v_lshl_add_u64 v[40:41], s[50:51], 0, v[0:1]
	v_lshl_add_u64 v[52:53], s[34:35], 0, v[48:49]
	v_lshl_add_u64 v[56:57], s[56:57], 0, v[48:49]
	global_load_dwordx4 v[0:3], v[4:5], off
	global_load_dwordx4 v[12:15], v[4:5], off offset:16
	global_load_dwordx4 v[24:27], v[4:5], off offset:32
	global_load_dwordx4 v[36:39], v[4:5], off offset:48
	global_load_dwordx4 v[8:11], v[6:7], off
	global_load_dwordx4 v[20:23], v[6:7], off offset:16
	global_load_dwordx4 v[32:35], v[6:7], off offset:32
	global_load_dwordx4 v[44:47], v[6:7], off offset:48
	s_nop 0
	global_load_dwordx4 v[4:7], v[40:41], off
	global_load_dwordx4 v[16:19], v[40:41], off offset:16
	global_load_dwordx4 v[28:31], v[40:41], off offset:32
	s_nop 0
	global_load_dwordx4 v[40:43], v[40:41], off offset:48
	v_lshl_add_u64 v[210:211], s[50:51], 0, v[48:49]
	global_load_dwordx4 v[48:51], v[52:53], off offset:48
	global_load_dwordx4 v[60:63], v[52:53], off offset:32
	global_load_dwordx4 v[194:197], v[52:53], off offset:16
	global_load_dwordx4 v[206:209], v[52:53], off
	s_nop 0
	global_load_dwordx4 v[52:55], v[56:57], off offset:48
	global_load_dwordx4 v[186:189], v[56:57], off offset:32
	global_load_dwordx4 v[198:201], v[56:57], off offset:16
	global_load_dwordx4 v[218:221], v[56:57], off
	s_nop 0
	global_load_dwordx4 v[56:59], v[210:211], off offset:48
	global_load_dwordx4 v[190:193], v[210:211], off offset:32
	global_load_dwordx4 v[202:205], v[210:211], off offset:16
	global_load_dwordx4 v[222:225], v[210:211], off
	s_cmp_lg_u32 s87, 0
	s_cbranch_scc1 .Lg1_skip
	v_readlane_b32 s0, v251, 47
	v_lshl_or_b32 v226, s1, 6, v216
	v_mul_u32_u24_e32 v226, 0xc0, v226
	v_mov_b32_e32 v232, s0
	v_readlane_b32 s0, v251, 48
	v_lshl_add_u32 v226, s2, 2, v226
	v_mov_b32_e32 v227, 0
	v_mov_b32_e32 v233, s0
	v_readlane_b32 s0, v255, 8
	v_lshl_add_u64 v[232:233], v[226:227], 0, v[232:233]
	s_mul_i32 s0, s0, 24
	s_add_i32 s0, s0, s2
	s_lshl_b32 s0, s0, 2
	global_load_dword v236, v[232:233], off
	global_load_dword v237, v[232:233], off offset:48
	v_mov_b32_e32 v226, s0
	global_load_dword v246, v[232:233], off offset:96
	global_load_dword v247, v[232:233], off offset:144
	global_load_dword v228, v226, s[70:71]
	global_load_dword v229, v226, s[70:71] offset:48
	global_load_dword v230, v226, s[68:69]
	global_load_dword v231, v226, s[68:69] offset:48
.Lg1_skip:
	s_waitcnt vmcnt(0)
	v_lshlrev_b32_e32 v212, 16, v178
	v_and_b32_e32 v213, 0xffff0000, v178
	v_lshlrev_b32_e32 v210, 16, v182
	v_and_b32_e32 v211, 0xffff0000, v182
	v_lshlrev_b32_e32 v178, 16, v179
	v_and_b32_e32 v179, 0xffff0000, v179
	v_lshlrev_b32_e32 v182, 16, v183
	v_and_b32_e32 v183, 0xffff0000, v183
	v_and_b32_e32 v214, 63, v216
	s_mov_b32 s0, 0x358637bd
	v_pk_mul_f32 v[212:213], v[218:219], v[212:213]
	s_nop 0
	v_pk_fma_f32 v[206:207], v[206:207], v[210:211], v[212:213]
	v_lshlrev_b32_e32 v210, 16, v174
	v_and_b32_e32 v211, 0xffff0000, v174
	v_pk_fma_f32 v[206:207], v[222:223], v[210:211], v[206:207]
	v_pk_mul_f32 v[178:179], v[220:221], v[178:179]
	v_mul_f32_e32 v174, 0xbfb8aa3b, v206
	v_exp_f32_e32 v174, v174
	v_pk_fma_f32 v[178:179], v[208:209], v[182:183], v[178:179]
	v_lshlrev_b32_e32 v182, 16, v180
	v_and_b32_e32 v183, 0xffff0000, v180
	v_add_f32_e32 v174, 1.0, v174
	v_rcp_f32_e32 v210, v174
	v_mul_f32_e32 v174, 0xbfb8aa3b, v207
	v_exp_f32_e32 v174, v174
	v_pk_mul_f32 v[182:183], v[198:199], v[182:183]
	v_lshlrev_b32_e32 v180, 16, v181
	v_and_b32_e32 v181, 0xffff0000, v181
	v_add_f32_e32 v174, 1.0, v174
	v_rcp_f32_e32 v211, v174
	v_lshlrev_b32_e32 v174, 16, v175
	v_and_b32_e32 v175, 0xffff0000, v175
	v_pk_fma_f32 v[174:175], v[224:225], v[174:175], v[178:179]
	v_pk_mul_f32 v[180:181], v[200:201], v[180:181]
	v_mul_f32_e32 v178, 0xbfb8aa3b, v174
	v_mul_f32_e32 v179, 0xbfb8aa3b, v175
	v_exp_f32_e32 v178, v178
	v_exp_f32_e32 v179, v179
	v_pk_mul_f32 v[212:213], v[206:207], v[210:211]
	v_add_f32_e32 v178, 1.0, v178
	v_add_f32_e32 v179, 1.0, v179
	v_rcp_f32_e32 v178, v178
	v_rcp_f32_e32 v179, v179
	s_nop 0
	v_pk_mul_f32 v[174:175], v[174:175], v[178:179]
	v_lshlrev_b32_e32 v178, 16, v184
	v_and_b32_e32 v179, 0xffff0000, v184
	v_pk_fma_f32 v[178:179], v[194:195], v[178:179], v[182:183]
	v_lshlrev_b32_e32 v182, 16, v176
	v_and_b32_e32 v183, 0xffff0000, v176
	v_pk_fma_f32 v[178:179], v[202:203], v[182:183], v[178:179]
	s_nop 0
	v_mul_f32_e32 v176, 0xbfb8aa3b, v178
	v_exp_f32_e32 v176, v176
	s_nop 0
	v_add_f32_e32 v176, 1.0, v176
	v_rcp_f32_e32 v182, v176
	v_mul_f32_e32 v176, 0xbfb8aa3b, v179
	v_exp_f32_e32 v176, v176
	s_nop 0
	v_add_f32_e32 v176, 1.0, v176
	v_rcp_f32_e32 v183, v176
	v_lshlrev_b32_e32 v176, 16, v177
	v_and_b32_e32 v177, 0xffff0000, v177
	v_pk_mul_f32 v[178:179], v[178:179], v[182:183]
	v_lshlrev_b32_e32 v182, 16, v185
	v_and_b32_e32 v183, 0xffff0000, v185
	v_pk_fma_f32 v[180:181], v[196:197], v[182:183], v[180:181]
	v_lshlrev_b32_e32 v182, 16, v124
	v_pk_fma_f32 v[176:177], v[204:205], v[176:177], v[180:181]
	v_and_b32_e32 v183, 0xffff0000, v124
	v_mul_f32_e32 v180, 0xbfb8aa3b, v176
	v_mul_f32_e32 v181, 0xbfb8aa3b, v177
	v_exp_f32_e32 v180, v180
	v_exp_f32_e32 v181, v181
	v_pk_mul_f32 v[182:183], v[186:187], v[182:183]
	v_add_u32_e32 v186, s87, v216
	v_add_f32_e32 v180, 1.0, v180
	v_add_f32_e32 v181, 1.0, v181
	v_rcp_f32_e32 v180, v180
	v_rcp_f32_e32 v181, v181
	v_ashrrev_i32_e32 v187, 3, v186
	v_pk_mul_f32 v[176:177], v[176:177], v[180:181]
	v_lshlrev_b32_e32 v180, 16, v134
	v_and_b32_e32 v181, 0xffff0000, v134
	v_pk_fma_f32 v[60:61], v[60:61], v[180:181], v[182:183]
	v_lshlrev_b32_e32 v180, 16, v146
	v_and_b32_e32 v181, 0xffff0000, v146
	v_pk_fma_f32 v[60:61], v[190:191], v[180:181], v[60:61]
	v_lshlrev_b32_e32 v134, 16, v135
	v_mul_f32_e32 v124, 0xbfb8aa3b, v60
	v_exp_f32_e32 v124, v124
	v_and_b32_e32 v135, 0xffff0000, v135
	v_add_f32_e32 v124, 1.0, v124
	v_rcp_f32_e32 v180, v124
	v_mul_f32_e32 v124, 0xbfb8aa3b, v61
	v_exp_f32_e32 v124, v124
	s_nop 0
	v_add_f32_e32 v124, 1.0, v124
	v_rcp_f32_e32 v181, v124
	v_lshlrev_b32_e32 v124, 16, v125
	v_and_b32_e32 v125, 0xffff0000, v125
	v_pk_mul_f32 v[124:125], v[188:189], v[124:125]
	v_pk_mul_f32 v[60:61], v[60:61], v[180:181]
	v_pk_fma_f32 v[62:63], v[62:63], v[134:135], v[124:125]
	v_lshlrev_b32_e32 v124, 16, v147
	v_and_b32_e32 v125, 0xffff0000, v147
	v_pk_fma_f32 v[62:63], v[192:193], v[124:125], v[62:63]
	v_lshlrev_b32_e32 v134, 16, v126
	v_mul_f32_e32 v124, 0xbfb8aa3b, v62
	v_mul_f32_e32 v125, 0xbfb8aa3b, v63
	v_exp_f32_e32 v124, v124
	v_exp_f32_e32 v125, v125
	v_and_b32_e32 v135, 0xffff0000, v126
	v_pk_mul_f32 v[52:53], v[52:53], v[134:135]
	v_add_f32_e32 v124, 1.0, v124
	v_add_f32_e32 v125, 1.0, v125
	v_rcp_f32_e32 v124, v124
	v_rcp_f32_e32 v125, v125
	s_nop 0
	v_pk_mul_f32 v[62:63], v[62:63], v[124:125]
	v_lshlrev_b32_e32 v124, 16, v136
	v_and_b32_e32 v125, 0xffff0000, v136
	v_pk_fma_f32 v[48:49], v[48:49], v[124:125], v[52:53]
	v_lshlrev_b32_e32 v52, 16, v148
	v_and_b32_e32 v53, 0xffff0000, v148
	v_pk_fma_f32 v[48:49], v[56:57], v[52:53], v[48:49]
	v_lshlrev_b32_e32 v56, 16, v127
	v_mul_f32_e32 v52, 0xbfb8aa3b, v48
	v_mul_f32_e32 v53, 0xbfb8aa3b, v49
	v_exp_f32_e32 v52, v52
	v_exp_f32_e32 v53, v53
	v_and_b32_e32 v57, 0xffff0000, v127
	v_pk_mul_f32 v[54:55], v[54:55], v[56:57]
	v_add_f32_e32 v52, 1.0, v52
	v_add_f32_e32 v53, 1.0, v53
	v_rcp_f32_e32 v52, v52
	v_rcp_f32_e32 v53, v53
	v_lshlrev_b32_e32 v124, 2, v214
	v_xor_b32_e32 v127, 4, v124
	v_xor_b32_e32 v126, 8, v124
	v_pk_mul_f32 v[48:49], v[48:49], v[52:53]
	v_lshlrev_b32_e32 v52, 16, v137
	v_and_b32_e32 v53, 0xffff0000, v137
	v_pk_fma_f32 v[50:51], v[50:51], v[52:53], v[54:55]
	v_lshlrev_b32_e32 v52, 16, v149
	v_and_b32_e32 v53, 0xffff0000, v149
	v_pk_fma_f32 v[50:51], v[58:59], v[52:53], v[50:51]
	v_lshlrev_b32_e32 v54, 16, v99
	v_mul_f32_e32 v52, 0xbfb8aa3b, v50
	v_mul_f32_e32 v53, 0xbfb8aa3b, v51
	v_exp_f32_e32 v52, v52
	v_exp_f32_e32 v53, v53
	v_and_b32_e32 v55, 0xffff0000, v99
	v_pk_mul_f32 v[54:55], v[168:169], v[54:55]
	v_add_f32_e32 v52, 1.0, v52
	v_add_f32_e32 v53, 1.0, v53
	v_rcp_f32_e32 v52, v52
	v_rcp_f32_e32 v53, v53
	v_lshlrev_b32_e32 v58, 16, v98
	v_and_b32_e32 v59, 0xffff0000, v98
	v_pk_mul_f32 v[58:59], v[166:167], v[58:59]
	v_pk_mul_f32 v[50:51], v[50:51], v[52:53]
	v_lshlrev_b32_e32 v52, 16, v107
	v_and_b32_e32 v53, 0xffff0000, v107
	v_pk_fma_f32 v[52:53], v[164:165], v[52:53], v[54:55]
	v_lshlrev_b32_e32 v54, 16, v111
	v_and_b32_e32 v55, 0xffff0000, v111
	v_pk_fma_f32 v[52:53], v[172:173], v[54:55], v[52:53]
	v_and_b32_e32 v107, 0xffff0000, v97
	v_mul_f32_e32 v54, 0xbfb8aa3b, v52
	v_mul_f32_e32 v55, 0xbfb8aa3b, v53
	v_exp_f32_e32 v54, v54
	v_exp_f32_e32 v55, v55
	v_and_b32_e32 v111, 0xffff0000, v104
	v_xor_b32_e32 v125, 16, v124
	v_add_f32_e32 v54, 1.0, v54
	v_add_f32_e32 v55, 1.0, v55
	v_rcp_f32_e32 v54, v54
	v_rcp_f32_e32 v55, v55
	s_nop 0
	v_pk_mul_f32 v[52:53], v[52:53], v[54:55]
	v_lshlrev_b32_e32 v54, 16, v106
	v_and_b32_e32 v55, 0xffff0000, v106
	v_pk_fma_f32 v[54:55], v[162:163], v[54:55], v[58:59]
	v_lshlrev_b32_e32 v58, 16, v110
	v_and_b32_e32 v59, 0xffff0000, v110
	v_pk_fma_f32 v[54:55], v[170:171], v[58:59], v[54:55]
	v_lshlrev_b32_e32 v106, 16, v97
	v_mul_f32_e32 v58, 0xbfb8aa3b, v54
	v_mul_f32_e32 v59, 0xbfb8aa3b, v55
	v_exp_f32_e32 v58, v58
	v_exp_f32_e32 v59, v59
	v_pk_mul_f32 v[106:107], v[156:157], v[106:107]
	v_lshlrev_b32_e32 v110, 16, v104
	v_add_f32_e32 v58, 1.0, v58
	v_add_f32_e32 v59, 1.0, v59
	v_rcp_f32_e32 v58, v58
	v_rcp_f32_e32 v59, v59
	v_lshlrev_b32_e32 v104, 16, v96
	v_pk_mul_f32 v[56:57], v[52:53], v[52:53]
	v_pk_mul_f32 v[54:55], v[54:55], v[58:59]
	v_lshlrev_b32_e32 v58, 16, v105
	v_and_b32_e32 v59, 0xffff0000, v105
	v_pk_fma_f32 v[58:59], v[152:153], v[58:59], v[106:107]
	v_lshlrev_b32_e32 v106, 16, v109
	v_and_b32_e32 v107, 0xffff0000, v109
	v_pk_fma_f32 v[58:59], v[160:161], v[106:107], v[58:59]
	v_and_b32_e32 v105, 0xffff0000, v96
	v_mul_f32_e32 v97, 0xbfb8aa3b, v58
	v_exp_f32_e32 v97, v97
	v_pk_mul_f32 v[98:99], v[54:55], v[54:55]
	v_add_f32_e32 v97, 1.0, v97
	v_rcp_f32_e32 v106, v97
	v_mul_f32_e32 v97, 0xbfb8aa3b, v59
	v_exp_f32_e32 v97, v97
	s_nop 0
	v_add_f32_e32 v97, 1.0, v97
	v_rcp_f32_e32 v107, v97
	v_pk_mul_f32 v[96:97], v[154:155], v[104:105]
	v_lshlrev_b32_e32 v104, 16, v108
	v_pk_fma_f32 v[96:97], v[150:151], v[110:111], v[96:97]
	v_and_b32_e32 v105, 0xffff0000, v108
	v_pk_fma_f32 v[96:97], v[158:159], v[104:105], v[96:97]
	v_lshlrev_b32_e32 v110, 16, v75
	v_mul_f32_e32 v104, 0xbfb8aa3b, v96
	v_mul_f32_e32 v105, 0xbfb8aa3b, v97
	v_exp_f32_e32 v104, v104
	v_exp_f32_e32 v105, v105
	v_and_b32_e32 v111, 0xffff0000, v75
	v_pk_mul_f32 v[110:111], v[140:141], v[110:111]
	v_add_f32_e32 v104, 1.0, v104
	v_add_f32_e32 v105, 1.0, v105
	v_rcp_f32_e32 v104, v104
	v_rcp_f32_e32 v105, v105
	v_pk_mul_f32 v[58:59], v[58:59], v[106:107]
	v_pk_mul_f32 v[96:97], v[96:97], v[104:105]
	v_lshlrev_b32_e32 v104, 16, v91
	v_and_b32_e32 v105, 0xffff0000, v91
	v_pk_fma_f32 v[104:105], v[132:133], v[104:105], v[110:111]
	v_lshlrev_b32_e32 v110, 16, v87
	v_and_b32_e32 v111, 0xffff0000, v87
	v_pk_fma_f32 v[104:105], v[144:145], v[110:111], v[104:105]
	v_and_b32_e32 v91, 0xffff0000, v74
	v_mul_f32_e32 v75, 0xbfb8aa3b, v104
	v_exp_f32_e32 v75, v75
	v_pk_mul_f32 v[108:109], v[96:97], v[96:97]
	v_pk_mul_f32 v[106:107], v[58:59], v[58:59]
	v_add_f32_e32 v75, 1.0, v75
	v_rcp_f32_e32 v110, v75
	v_mul_f32_e32 v75, 0xbfb8aa3b, v105
	v_exp_f32_e32 v75, v75
	s_nop 0
	v_add_f32_e32 v75, 1.0, v75
	v_rcp_f32_e32 v111, v75
	s_nop 0
	v_pk_mul_f32 v[104:105], v[104:105], v[110:111]
	v_lshlrev_b32_e32 v110, 16, v90
	v_and_b32_e32 v111, 0xffff0000, v90
	v_lshlrev_b32_e32 v90, 16, v74
	v_pk_mul_f32 v[74:75], v[138:139], v[90:91]
	v_lshlrev_b32_e32 v90, 16, v86
	v_pk_fma_f32 v[74:75], v[130:131], v[110:111], v[74:75]
	v_and_b32_e32 v91, 0xffff0000, v86
	v_pk_fma_f32 v[74:75], v[142:143], v[90:91], v[74:75]
	v_lshlrev_b32_e32 v90, 16, v73
	v_mul_f32_e32 v86, 0xbfb8aa3b, v74
	v_mul_f32_e32 v87, 0xbfb8aa3b, v75
	v_exp_f32_e32 v86, v86
	v_exp_f32_e32 v87, v87
	v_and_b32_e32 v91, 0xffff0000, v73
	v_pk_mul_f32 v[90:91], v[118:119], v[90:91]
	v_add_f32_e32 v86, 1.0, v86
	v_add_f32_e32 v87, 1.0, v87
	v_rcp_f32_e32 v86, v86
	v_rcp_f32_e32 v87, v87
	s_nop 0
	v_pk_mul_f32 v[74:75], v[74:75], v[86:87]
	v_lshlrev_b32_e32 v86, 16, v89
	v_and_b32_e32 v87, 0xffff0000, v89
	v_pk_fma_f32 v[86:87], v[114:115], v[86:87], v[90:91]
	v_lshlrev_b32_e32 v90, 16, v85
	v_and_b32_e32 v91, 0xffff0000, v85
	v_pk_fma_f32 v[86:87], v[122:123], v[90:91], v[86:87]
	v_and_b32_e32 v89, 0xffff0000, v72
	v_mul_f32_e32 v73, 0xbfb8aa3b, v86
	v_exp_f32_e32 v73, v73
	s_nop 0
	v_add_f32_e32 v73, 1.0, v73
	v_rcp_f32_e32 v90, v73
	v_mul_f32_e32 v73, 0xbfb8aa3b, v87
	v_exp_f32_e32 v73, v73
	s_nop 0
	v_add_f32_e32 v73, 1.0, v73
	v_rcp_f32_e32 v91, v73
	s_nop 0
	v_pk_mul_f32 v[86:87], v[86:87], v[90:91]
	v_lshlrev_b32_e32 v90, 16, v88
	v_and_b32_e32 v91, 0xffff0000, v88
	v_lshlrev_b32_e32 v88, 16, v72
	v_pk_mul_f32 v[72:73], v[116:117], v[88:89]
	v_lshlrev_b32_e32 v88, 16, v84
	v_pk_fma_f32 v[72:73], v[112:113], v[90:91], v[72:73]
	v_and_b32_e32 v89, 0xffff0000, v84
	v_pk_fma_f32 v[72:73], v[120:121], v[88:89], v[72:73]
	v_lshlrev_b32_e32 v88, 16, v83
	v_mul_f32_e32 v84, 0xbfb8aa3b, v72
	v_mul_f32_e32 v85, 0xbfb8aa3b, v73
	v_exp_f32_e32 v84, v84
	v_exp_f32_e32 v85, v85
	v_and_b32_e32 v89, 0xffff0000, v83
	v_pk_mul_f32 v[46:47], v[46:47], v[88:89]
	v_add_f32_e32 v84, 1.0, v84
	v_add_f32_e32 v85, 1.0, v85
	v_rcp_f32_e32 v84, v84
	v_rcp_f32_e32 v85, v85
	s_nop 0
	v_pk_mul_f32 v[72:73], v[72:73], v[84:85]
	v_lshlrev_b32_e32 v84, 16, v95
	v_and_b32_e32 v85, 0xffff0000, v95
	v_pk_fma_f32 v[38:39], v[38:39], v[84:85], v[46:47]
	v_lshlrev_b32_e32 v46, 16, v103
	v_and_b32_e32 v47, 0xffff0000, v103
	v_lshlrev_b32_e32 v84, 16, v82
	v_and_b32_e32 v85, 0xffff0000, v82
	v_pk_fma_f32 v[38:39], v[42:43], v[46:47], v[38:39]
	v_lshlrev_b32_e32 v46, 16, v94
	v_and_b32_e32 v47, 0xffff0000, v94
	v_pk_mul_f32 v[44:45], v[44:45], v[84:85]
	v_mul_f32_e32 v42, 0xbfb8aa3b, v38
	v_pk_fma_f32 v[36:37], v[36:37], v[46:47], v[44:45]
	v_lshlrev_b32_e32 v44, 16, v102
	v_and_b32_e32 v45, 0xffff0000, v102
	v_lshlrev_b32_e32 v46, 16, v81
	v_and_b32_e32 v47, 0xffff0000, v81
	v_pk_fma_f32 v[36:37], v[40:41], v[44:45], v[36:37]
	v_lshlrev_b32_e32 v44, 16, v93
	v_and_b32_e32 v45, 0xffff0000, v93
	v_pk_mul_f32 v[34:35], v[34:35], v[46:47]
	v_mul_f32_e32 v40, 0xbfb8aa3b, v36
	v_pk_fma_f32 v[26:27], v[26:27], v[44:45], v[34:35]
	v_lshlrev_b32_e32 v34, 16, v101
	v_and_b32_e32 v35, 0xffff0000, v101
	v_lshlrev_b32_e32 v44, 16, v80
	v_and_b32_e32 v45, 0xffff0000, v80
	v_pk_fma_f32 v[26:27], v[30:31], v[34:35], v[26:27]
	v_lshlrev_b32_e32 v34, 16, v92
	v_and_b32_e32 v35, 0xffff0000, v92
	v_pk_mul_f32 v[32:33], v[32:33], v[44:45]
	v_mul_f32_e32 v30, 0xbfb8aa3b, v26
	v_pk_fma_f32 v[24:25], v[24:25], v[34:35], v[32:33]
	v_lshlrev_b32_e32 v32, 16, v100
	v_and_b32_e32 v33, 0xffff0000, v100
	v_lshlrev_b32_e32 v34, 16, v67
	v_and_b32_e32 v35, 0xffff0000, v67
	v_pk_fma_f32 v[24:25], v[28:29], v[32:33], v[24:25]
	v_lshlrev_b32_e32 v32, 16, v71
	v_and_b32_e32 v33, 0xffff0000, v71
	v_pk_mul_f32 v[22:23], v[22:23], v[34:35]
	v_mul_f32_e32 v28, 0xbfb8aa3b, v24
	v_pk_fma_f32 v[14:15], v[14:15], v[32:33], v[22:23]
	v_lshlrev_b32_e32 v22, 16, v79
	v_and_b32_e32 v23, 0xffff0000, v79
	v_pk_fma_f32 v[14:15], v[18:19], v[22:23], v[14:15]
	v_lshlrev_b32_e32 v22, 16, v66
	v_mul_f32_e32 v18, 0xbfb8aa3b, v14
	v_mul_f32_e32 v19, 0xbfb8aa3b, v15
	v_exp_f32_e32 v18, v18
	v_exp_f32_e32 v19, v19
	v_and_b32_e32 v23, 0xffff0000, v66
	v_pk_mul_f32 v[20:21], v[20:21], v[22:23]
	v_add_f32_e32 v18, 1.0, v18
	v_add_f32_e32 v19, 1.0, v19
	v_rcp_f32_e32 v18, v18
	v_rcp_f32_e32 v19, v19
	v_mul_f32_e32 v29, 0xbfb8aa3b, v25
	v_exp_f32_e32 v28, v28
	v_exp_f32_e32 v29, v29
	v_pk_mul_f32 v[14:15], v[14:15], v[18:19]
	v_lshlrev_b32_e32 v18, 16, v70
	v_and_b32_e32 v19, 0xffff0000, v70
	v_pk_fma_f32 v[12:13], v[12:13], v[18:19], v[20:21]
	v_lshlrev_b32_e32 v18, 16, v78
	v_and_b32_e32 v19, 0xffff0000, v78
	v_pk_fma_f32 v[12:13], v[16:17], v[18:19], v[12:13]
	v_lshlrev_b32_e32 v18, 16, v65
	v_mul_f32_e32 v16, 0xbfb8aa3b, v12
	v_mul_f32_e32 v17, 0xbfb8aa3b, v13
	v_exp_f32_e32 v16, v16
	v_exp_f32_e32 v17, v17
	v_and_b32_e32 v19, 0xffff0000, v65
	v_pk_mul_f32 v[10:11], v[10:11], v[18:19]
	v_add_f32_e32 v16, 1.0, v16
	v_add_f32_e32 v17, 1.0, v17
	v_rcp_f32_e32 v16, v16
	v_rcp_f32_e32 v17, v17
	v_mul_f32_e32 v31, 0xbfb8aa3b, v27
	v_exp_f32_e32 v30, v30
	v_exp_f32_e32 v31, v31
	v_pk_mul_f32 v[12:13], v[12:13], v[16:17]
	v_lshlrev_b32_e32 v16, 16, v69
	v_and_b32_e32 v17, 0xffff0000, v69
	v_pk_fma_f32 v[2:3], v[2:3], v[16:17], v[10:11]
	v_lshlrev_b32_e32 v10, 16, v77
	v_and_b32_e32 v11, 0xffff0000, v77
	v_pk_fma_f32 v[2:3], v[6:7], v[10:11], v[2:3]
	v_lshlrev_b32_e32 v10, 16, v64
	v_mul_f32_e32 v6, 0xbfb8aa3b, v2
	v_mul_f32_e32 v7, 0xbfb8aa3b, v3
	v_exp_f32_e32 v6, v6
	v_exp_f32_e32 v7, v7
	v_and_b32_e32 v11, 0xffff0000, v64
	v_pk_mul_f32 v[8:9], v[8:9], v[10:11]
	v_add_f32_e32 v6, 1.0, v6
	v_add_f32_e32 v7, 1.0, v7
	v_rcp_f32_e32 v6, v6
	v_rcp_f32_e32 v7, v7
	v_mul_f32_e32 v41, 0xbfb8aa3b, v37
	v_mov_b32_e32 v23, v73
	v_exp_f32_e32 v40, v40
	v_pk_mul_f32 v[2:3], v[2:3], v[6:7]
	v_lshlrev_b32_e32 v6, 16, v68
	v_and_b32_e32 v7, 0xffff0000, v68
	v_pk_fma_f32 v[0:1], v[0:1], v[6:7], v[8:9]
	v_lshlrev_b32_e32 v6, 16, v76
	v_and_b32_e32 v7, 0xffff0000, v76
	v_pk_fma_f32 v[0:1], v[4:5], v[6:7], v[0:1]
	v_exp_f32_e32 v41, v41
	v_mul_f32_e32 v4, 0xbfb8aa3b, v0
	v_mul_f32_e32 v5, 0xbfb8aa3b, v1
	v_exp_f32_e32 v4, v4
	v_exp_f32_e32 v5, v5
	v_add_f32_e32 v28, 1.0, v28
	v_add_f32_e32 v29, 1.0, v29
	v_add_f32_e32 v4, 1.0, v4
	v_add_f32_e32 v5, 1.0, v5
	v_rcp_f32_e32 v4, v4
	v_rcp_f32_e32 v5, v5
	v_mov_b32_e32 v21, v72
	v_mul_f32_e32 v43, 0xbfb8aa3b, v39
	v_rcp_f32_e32 v28, v28
	v_pk_mul_f32 v[0:1], v[0:1], v[4:5]
	v_rcp_f32_e32 v29, v29
	v_mov_b32_e32 v22, v1
	v_mov_b32_e32 v20, v0
	v_pk_mul_f32 v[22:23], v[22:23], v[22:23]
	v_mov_b32_e32 v16, v2
	v_mov_b32_e32 v17, v86
	v_pk_fma_f32 v[20:21], v[20:21], v[20:21], v[22:23]
	v_exp_f32_e32 v42, v42
	v_exp_f32_e32 v43, v43
	v_add_f32_e32 v30, 1.0, v30
	v_add_f32_e32 v31, 1.0, v31
	v_mov_b32_e32 v18, v3
	v_mov_b32_e32 v19, v87
	v_pk_fma_f32 v[16:17], v[16:17], v[16:17], v[20:21]
	v_rcp_f32_e32 v30, v30
	v_rcp_f32_e32 v31, v31
	v_mov_b32_e32 v8, v12
	v_mov_b32_e32 v9, v74
	v_pk_fma_f32 v[16:17], v[18:19], v[18:19], v[16:17]
	v_add_f32_e32 v40, 1.0, v40
	v_add_f32_e32 v41, 1.0, v41
	v_mov_b32_e32 v10, v13
	v_mov_b32_e32 v11, v75
	v_pk_fma_f32 v[8:9], v[8:9], v[8:9], v[16:17]
	v_rcp_f32_e32 v40, v40
	v_rcp_f32_e32 v41, v41
	v_pk_mul_f32 v[24:25], v[24:25], v[28:29]
	v_mov_b32_e32 v4, v14
	v_mov_b32_e32 v5, v104
	v_pk_fma_f32 v[8:9], v[10:11], v[10:11], v[8:9]
	v_add_f32_e32 v42, 1.0, v42
	v_add_f32_e32 v43, 1.0, v43
	v_pk_mul_f32 v[28:29], v[24:25], v[24:25]
	v_mov_b32_e32 v6, v15
	v_mov_b32_e32 v7, v105
	v_pk_fma_f32 v[4:5], v[4:5], v[4:5], v[8:9]
	v_rcp_f32_e32 v42, v42
	v_rcp_f32_e32 v43, v43
	v_pk_mul_f32 v[26:27], v[26:27], v[30:31]
	v_pk_fma_f32 v[4:5], v[6:7], v[6:7], v[4:5]
	v_mov_b32_e32 v6, v28
	v_mov_b32_e32 v7, v108
	v_pk_mul_f32 v[30:31], v[26:27], v[26:27]
	v_pk_add_f32 v[4:5], v[6:7], v[4:5]
	v_mov_b32_e32 v108, v29
	v_pk_mul_f32 v[36:37], v[36:37], v[40:41]
	v_pk_add_f32 v[4:5], v[108:109], v[4:5]
	v_mov_b32_e32 v6, v30
	v_mov_b32_e32 v7, v106
	v_pk_mul_f32 v[40:41], v[36:37], v[36:37]
	v_pk_add_f32 v[4:5], v[6:7], v[4:5]
	v_mov_b32_e32 v106, v31
	v_pk_mul_f32 v[38:39], v[38:39], v[42:43]
	v_pk_add_f32 v[4:5], v[106:107], v[4:5]
	v_mov_b32_e32 v6, v40
	v_mov_b32_e32 v7, v98
	v_pk_mul_f32 v[42:43], v[38:39], v[38:39]
	v_pk_add_f32 v[4:5], v[6:7], v[4:5]
	v_mov_b32_e32 v98, v41
	v_pk_add_f32 v[4:5], v[98:99], v[4:5]
	v_mov_b32_e32 v6, v42
	v_mov_b32_e32 v7, v56
	v_pk_add_f32 v[4:5], v[6:7], v[4:5]
	v_mov_b32_e32 v56, v43
	v_pk_add_f32 v[4:5], v[56:57], v[4:5]
	ds_bpermute_b32 v7, v127, v5
	ds_bpermute_b32 v6, v127, v4
	s_waitcnt lgkmcnt(0)
	v_pk_add_f32 v[4:5], v[4:5], v[6:7]
	ds_bpermute_b32 v7, v126, v5
	ds_bpermute_b32 v6, v126, v4
	s_waitcnt lgkmcnt(0)
	v_pk_add_f32 v[4:5], v[4:5], v[6:7]
	ds_bpermute_b32 v7, v125, v5
	ds_bpermute_b32 v6, v125, v4
	s_waitcnt lgkmcnt(0)
	v_pk_add_f32 v[4:5], v[4:5], v[6:7]
	s_nop 0
	v_pk_add_f32 v[16:17], v[4:5], s[0:1] op_sel_hi:[1,0]
	s_movk_i32 s0, 0x70
	v_mul_f32_e32 v4, 0x4b800000, v17
	v_cmp_gt_f32_e64 s[38:39], s25, v17
	v_cmp_gt_f32_e32 vcc, s25, v16
	s_nop 0
	v_cndmask_b32_e64 v4, v17, v4, s[38:39]
	v_mul_f32_e32 v17, 0x4b800000, v16
	v_cndmask_b32_e32 v16, v16, v17, vcc
	v_rsq_f32_e32 v16, v16
	v_rsq_f32_e32 v4, v4
	v_mul_f32_e32 v17, 0x45800000, v16
	v_mul_f32_e32 v5, 0x45800000, v4
	v_cndmask_b32_e32 v16, v16, v17, vcc
	v_cndmask_b32_e64 v4, v4, v5, s[38:39]
	v_pk_mul_f32 v[0:1], v[0:1], v[16:17] op_sel_hi:[1,0]
	v_pk_mul_f32 v[2:3], v[2:3], v[16:17] op_sel_hi:[1,0]
	v_mul_f32_e32 v18, 0x3db504f3, v4
	v_cvt_pk_bf16_f32 v0, v0, v1
	v_cvt_pk_bf16_f32 v1, v2, v3
	v_pk_mul_f32 v[2:3], v[12:13], v[16:17] op_sel_hi:[1,0]
	v_pk_mul_f32 v[12:13], v[14:15], v[16:17] op_sel_hi:[1,0]
	v_pk_mul_f32 v[4:5], v[72:73], v[18:19] op_sel_hi:[1,0]
	v_pk_mul_f32 v[6:7], v[86:87], v[18:19] op_sel_hi:[1,0]
	v_cvt_pk_bf16_f32 v2, v2, v3
	v_cvt_pk_bf16_f32 v3, v12, v13
	v_pk_mul_f32 v[12:13], v[24:25], v[16:17] op_sel_hi:[1,0]
	v_pk_mul_f32 v[14:15], v[26:27], v[16:17] op_sel_hi:[1,0]
	v_cvt_pk_bf16_f32 v4, v4, v5
	v_cvt_pk_bf16_f32 v5, v6, v7
	v_pk_mul_f32 v[6:7], v[74:75], v[18:19] op_sel_hi:[1,0]
	v_pk_mul_f32 v[8:9], v[104:105], v[18:19] op_sel_hi:[1,0]
	v_cvt_pk_bf16_f32 v12, v12, v13
	v_cvt_pk_bf16_f32 v13, v14, v15
	v_pk_mul_f32 v[14:15], v[36:37], v[16:17] op_sel_hi:[1,0]
	v_pk_mul_f32 v[16:17], v[38:39], v[16:17] op_sel_hi:[1,0]
	v_cvt_pk_bf16_f32 v6, v6, v7
	v_cvt_pk_bf16_f32 v7, v8, v9
	v_pk_mul_f32 v[8:9], v[96:97], v[18:19] op_sel_hi:[1,0]
	v_pk_mul_f32 v[10:11], v[58:59], v[18:19] op_sel_hi:[1,0]
	v_cvt_pk_bf16_f32 v14, v14, v15
	v_cvt_pk_bf16_f32 v15, v16, v17
	v_mul_lo_u32 v16, v187, s96
	v_lshlrev_b32_e32 v17, 5, v128
	v_cvt_pk_bf16_f32 v8, v8, v9
	v_cvt_pk_bf16_f32 v9, v10, v11
	v_pk_mul_f32 v[10:11], v[54:55], v[18:19] op_sel_hi:[1,0]
	v_pk_mul_f32 v[18:19], v[52:53], v[18:19] op_sel_hi:[1,0]
	v_add3_u32 v16, 0, v16, v17
	v_cvt_pk_bf16_f32 v10, v10, v11
	v_cvt_pk_bf16_f32 v11, v18, v19
	ds_write_b128 v16, v[4:7] offset:17408
	ds_write_b128 v16, v[8:11] offset:17424
	ds_write_b128 v16, v[0:3]
	ds_write_b128 v16, v[12:15] offset:16
	v_lshrrev_b32_e32 v4, 6, v186
	v_xor_b32_e32 v4, v4, v216
	v_lshlrev_b32_e32 v5, 1, v187
	v_lshlrev_b32_e32 v4, 4, v4
	v_and_b32_e32 v5, 14, v5
	v_and_or_b32 v4, v4, s0, v5
	v_mul_u32_u24_e32 v5, 0x900, v128
	v_add3_u32 v4, 0, v4, v5
	ds_write_b16 v4, v0 offset:34816
	ds_write_b16_d16_hi v4, v0 offset:34960
	v_cvt_pk_bf16_f32 v0, v212, v213
	ds_write_b16 v4, v0 offset:53248
	ds_write_b16_d16_hi v4, v0 offset:53392
	ds_write_b16 v4, v1 offset:35104
	ds_write_b16_d16_hi v4, v1 offset:35248
	v_cvt_pk_bf16_f32 v0, v174, v175
	ds_write_b16 v4, v0 offset:53536
	ds_write_b16_d16_hi v4, v0 offset:53680
	ds_write_b16 v4, v2 offset:35392
	ds_write_b16_d16_hi v4, v2 offset:35536
	v_cvt_pk_bf16_f32 v0, v178, v179
	ds_write_b16 v4, v0 offset:53824
	ds_write_b16_d16_hi v4, v0 offset:53968
	ds_write_b16 v4, v3 offset:35680
	ds_write_b16_d16_hi v4, v3 offset:35824
	v_cvt_pk_bf16_f32 v0, v176, v177
	ds_write_b16 v4, v0 offset:54112
	ds_write_b16_d16_hi v4, v0 offset:54256
	ds_write_b16 v4, v12 offset:35968
	ds_write_b16_d16_hi v4, v12 offset:36112
	v_cvt_pk_bf16_f32 v0, v60, v61
	ds_write_b16 v4, v0 offset:54400
	ds_write_b16_d16_hi v4, v0 offset:54544
	ds_write_b16 v4, v13 offset:36256
	ds_write_b16_d16_hi v4, v13 offset:36400
	v_cvt_pk_bf16_f32 v0, v62, v63
	ds_write_b16 v4, v0 offset:54688
	ds_write_b16_d16_hi v4, v0 offset:54832
	ds_write_b16 v4, v14 offset:36544
	ds_write_b16_d16_hi v4, v14 offset:36688
	v_cvt_pk_bf16_f32 v0, v48, v49
	ds_write_b16 v4, v0 offset:54976
	ds_write_b16_d16_hi v4, v0 offset:55120
	ds_write_b16 v4, v15 offset:36832
	ds_write_b16_d16_hi v4, v15 offset:36976
	v_cvt_pk_bf16_f32 v0, v50, v51
	v_cmp_gt_u32_e64 s[38:39], 64, v186
	ds_write_b16 v4, v0 offset:55264
	ds_write_b16_d16_hi v4, v0 offset:55408
	s_and_saveexec_b64 s[4:5], s[38:39]
	s_cbranch_execz .LBB0_194
	v_lshl_or_b32 v2, s1, 6, v186
	v_readlane_b32 s0, v251, 47
	v_readlane_b32 s1, v251, 48
	s_ashr_i32 s3, s2, 31
	s_mov_b32 s8, 0xc2ce8ed0
	v_mov_b64_e32 v[0:1], s[0:1]
	s_movk_i32 s0, 0xc0
	v_mad_i64_i32 v[0:1], s[0:1], v2, s0, v[0:1]
	v_readlane_b32 s0, v255, 8
	s_mul_i32 s0, s0, 24
	v_readlane_b32 s1, v255, 9
	s_add_i32 s0, s2, s0
	s_ashr_i32 s1, s0, 31
	s_lshl_b64 s[6:7], s[0:1], 2
	v_lshl_add_u64 v[0:1], s[2:3], 2, v[0:1]
	s_add_u32 s2, s70, s6
	s_addc_u32 s3, s71, s7
	v_mov_b32_e32 v2, v236
	v_mov_b32_e32 v3, v228
	s_add_i32 s0, s0, 12
	s_ashr_i32 s1, s0, 31
	s_lshl_b64 s[2:3], s[0:1], 2
	s_add_u32 s0, s70, s2
	s_addc_u32 s1, s71, s3
	v_mov_b32_e32 v4, v229
	s_add_u32 s0, s68, s6
	s_addc_u32 s1, s69, s7
	s_mov_b32 s7, 0x3fb8aa3b
	s_mov_b32 s9, 0x42b17218
	s_mov_b32 s6, 0xbfb8aa3b
	s_mov_b32 s10, 0xb2a5705f
	s_mov_b32 s11, 0x42ce8ed0
	s_mov_b32 s16, 0xc2b17218
	s_mov_b32 s17, 0x3f2aaaab
	s_mov_b32 s26, 0x3f317218
	s_mov_b32 s27, 0x33800000
	v_cmp_gt_u32_e64 s[42:43], 60, v214
	s_waitcnt vmcnt(1)
	v_add_f32_e32 v3, v2, v3
	v_mov_b32_e32 v2, v237
	s_waitcnt vmcnt(0)
	v_add_f32_e32 v6, v2, v4
	v_mov_b32_e32 v2, v230
	s_add_u32 s0, s68, s2
	s_addc_u32 s1, s69, s3
	v_readlane_b32 s2, v254, 41
	s_waitcnt vmcnt(0)
	v_mul_f32_e32 v4, 0x3fb8aa3b, v2
	v_fma_f32 v5, v2, s7, -v4
	v_rndne_f32_e32 v7, v4
	v_fmac_f32_e32 v5, 0x32a5705f, v2
	v_sub_f32_e32 v4, v4, v7
	v_add_f32_e32 v4, v4, v5
	v_exp_f32_e32 v4, v4
	v_cvt_i32_f32_e32 v5, v7
	v_cmp_ngt_f32_e32 vcc, s8, v2
	v_max_f32_e32 v7, 0, v3
	v_ldexp_f32 v4, v4, v5
	v_cndmask_b32_e32 v4, 0, v4, vcc
	v_cmp_nlt_f32_e32 vcc, s9, v2
	s_nop 1
	v_cndmask_b32_e32 v2, v249, v4, vcc
	v_mul_f32_e64 v4, |v3|, s6
	v_fma_f32 v5, |v3|, s6, -v4
	v_rndne_f32_e32 v8, v4
	v_fma_f32 v5, |v3|, s10, v5
	v_sub_f32_e32 v4, v4, v8
	v_add_f32_e32 v4, v4, v5
	v_exp_f32_e32 v4, v4
	v_cvt_i32_f32_e32 v5, v8
	v_cmp_ngt_f32_e64 vcc, |v3|, s11
	v_ldexp_f32 v4, v4, v5
	s_nop 0
	v_cndmask_b32_e32 v4, 0, v4, vcc
	v_cmp_nlt_f32_e64 vcc, |v3|, s16
	s_nop 1
	v_cndmask_b32_e32 v3, v249, v4, vcc
	v_add_f32_e32 v8, 1.0, v3
	v_add_f32_e32 v4, -1.0, v8
	v_sub_f32_e32 v5, v4, v8
	v_add_f32_e32 v5, 1.0, v5
	v_sub_f32_e32 v4, v3, v4
	v_add_f32_e32 v9, v4, v5
	v_frexp_mant_f32_e32 v4, v8
	v_cmp_gt_f32_e32 vcc, s17, v4
	v_cvt_f64_f32_e32 v[4:5], v8
	v_frexp_exp_i32_f64_e32 v4, v[4:5]
	v_subbrev_co_u32_e32 v4, vcc, 0, v4, vcc
	v_sub_u32_e32 v5, 0, v4
	v_ldexp_f32 v8, v8, v5
	v_ldexp_f32 v5, v9, v5
	v_add_f32_e32 v9, -1.0, v8
	v_add_f32_e32 v10, 1.0, v9
	v_sub_f32_e32 v10, v8, v10
	v_add_f32_e32 v10, v5, v10
	v_add_f32_e32 v11, v9, v10
	v_sub_f32_e32 v9, v9, v11
	v_add_f32_e32 v9, v10, v9
	v_add_f32_e32 v10, 1.0, v8
	v_add_f32_e32 v12, -1.0, v10
	v_sub_f32_e32 v8, v8, v12
	v_add_f32_e32 v5, v5, v8
	v_add_f32_e32 v8, v10, v5
	v_sub_f32_e32 v10, v10, v8
	v_add_f32_e32 v5, v5, v10
	v_rcp_f32_e32 v10, v8
	v_cvt_f32_i32_e32 v4, v4
	v_cmp_neq_f32_e32 vcc, s33, v3
	v_mul_f32_e32 v12, v11, v10
	v_mul_f32_e32 v13, v8, v12
	v_fma_f32 v14, v12, v8, -v13
	v_fmac_f32_e32 v14, v12, v5
	v_add_f32_e32 v15, v13, v14
	v_sub_f32_e32 v16, v11, v15
	v_sub_f32_e32 v11, v11, v16
	v_sub_f32_e32 v13, v15, v13
	v_sub_f32_e32 v11, v11, v15
	v_add_f32_e32 v9, v9, v11
	v_sub_f32_e32 v11, v13, v14
	v_add_f32_e32 v9, v11, v9
	v_add_f32_e32 v11, v16, v9
	v_mul_f32_e32 v13, v10, v11
	v_mul_f32_e32 v14, v8, v13
	v_fma_f32 v8, v13, v8, -v14
	v_fmac_f32_e32 v8, v13, v5
	v_sub_f32_e32 v5, v16, v11
	v_add_f32_e32 v5, v9, v5
	v_add_f32_e32 v9, v14, v8
	v_sub_f32_e32 v15, v11, v9
	v_sub_f32_e32 v11, v11, v15
	v_sub_f32_e32 v14, v9, v14
	v_sub_f32_e32 v9, v11, v9
	v_add_f32_e32 v5, v5, v9
	v_sub_f32_e32 v8, v14, v8
	v_add_f32_e32 v5, v8, v5
	v_add_f32_e32 v8, v12, v13
	v_add_f32_e32 v5, v15, v5
	v_sub_f32_e32 v9, v8, v12
	v_mul_f32_e32 v5, v10, v5
	v_sub_f32_e32 v9, v13, v9
	v_add_f32_e32 v5, v9, v5
	v_mul_f32_e32 v12, 0x3f317218, v4
	v_add_f32_e32 v9, v8, v5
	v_fma_f32 v13, v4, s26, -v12
	v_mul_f32_e32 v10, v9, v9
	v_fmac_f32_e32 v13, 0xb102e308, v4
	v_sub_f32_e32 v4, v9, v8
	v_fmamk_f32 v11, v10, 0x3e9b6dac, v238
	v_sub_f32_e32 v4, v5, v4
	v_add_f32_e32 v5, v12, v13
	v_fmaak_f32 v11, v10, v11, 0x3f2aaada
	v_sub_f32_e32 v8, v5, v12
	v_ldexp_f32 v12, v9, 1
	v_mul_f32_e32 v9, v9, v10
	v_mul_f32_e32 v9, v9, v11
	v_add_f32_e32 v10, v12, v9
	v_sub_f32_e32 v11, v10, v12
	v_ldexp_f32 v4, v4, 1
	v_sub_f32_e32 v9, v9, v11
	v_add_f32_e32 v4, v4, v9
	v_add_f32_e32 v9, v10, v4
	v_sub_f32_e32 v10, v9, v10
	v_sub_f32_e32 v4, v4, v10
	v_add_f32_e32 v10, v5, v9
	v_sub_f32_e32 v11, v10, v5
	v_sub_f32_e32 v12, v10, v11
	v_sub_f32_e32 v8, v13, v8
	v_sub_f32_e32 v5, v5, v12
	v_sub_f32_e32 v9, v9, v11
	v_add_f32_e32 v5, v9, v5
	v_add_f32_e32 v9, v8, v4
	v_sub_f32_e32 v11, v9, v8
	v_sub_f32_e32 v12, v9, v11
	v_sub_f32_e32 v8, v8, v12
	v_sub_f32_e32 v4, v4, v11
	v_add_f32_e32 v5, v9, v5
	v_add_f32_e32 v4, v4, v8
	v_add_f32_e32 v8, v10, v5
	v_sub_f32_e32 v9, v8, v10
	v_sub_f32_e32 v5, v5, v9
	v_add_f32_e32 v4, v4, v5
	v_mov_b32_e32 v5, v231
	v_add_f32_e32 v4, v8, v4
	v_cndmask_b32_e32 v4, v249, v4, vcc
	v_cmp_lt_f32_e64 vcc, |v3|, s27
	s_nop 1
	v_cndmask_b32_e32 v3, v4, v3, vcc
	v_add_f32_e32 v3, v7, v3
	v_mul_f32_e64 v4, v3, -v2
	s_waitcnt vmcnt(0)
	v_mul_f32_e32 v7, 0x3fb8aa3b, v5
	v_fma_f32 v8, v5, s7, -v7
	v_rndne_f32_e32 v9, v7
	v_fmac_f32_e32 v8, 0x32a5705f, v5
	v_sub_f32_e32 v7, v7, v9
	v_add_f32_e32 v7, v7, v8
	v_exp_f32_e32 v7, v7
	v_cvt_i32_f32_e32 v8, v9
	v_cmp_ngt_f32_e32 vcc, s8, v5
	v_ldexp_f32 v7, v7, v8
	s_nop 0
	v_cndmask_b32_e32 v7, 0, v7, vcc
	v_cmp_nlt_f32_e32 vcc, s9, v5
	v_max_f32_e32 v8, 0, v6
	s_nop 0
	v_cndmask_b32_e32 v5, v249, v7, vcc
	v_mul_f32_e64 v7, |v6|, s6
	v_fma_f32 v9, |v6|, s6, -v7
	v_rndne_f32_e32 v10, v7
	v_fma_f32 v9, |v6|, s10, v9
	v_sub_f32_e32 v7, v7, v10
	v_add_f32_e32 v7, v7, v9
	v_exp_f32_e32 v7, v7
	v_cvt_i32_f32_e32 v9, v10
	v_cmp_ngt_f32_e64 vcc, |v6|, s11
	v_ldexp_f32 v7, v7, v9
	s_nop 0
	v_cndmask_b32_e32 v7, 0, v7, vcc
	v_cmp_nlt_f32_e64 vcc, |v6|, s16
	s_nop 1
	v_cndmask_b32_e32 v9, v249, v7, vcc
	v_add_f32_e32 v10, 1.0, v9
	v_add_f32_e32 v6, -1.0, v10
	v_sub_f32_e32 v7, v6, v10
	v_add_f32_e32 v7, 1.0, v7
	v_sub_f32_e32 v6, v9, v6
	v_add_f32_e32 v11, v6, v7
	v_frexp_mant_f32_e32 v6, v10
	v_cmp_gt_f32_e32 vcc, s17, v6
	v_cvt_f64_f32_e32 v[6:7], v10
	v_frexp_exp_i32_f64_e32 v6, v[6:7]
	v_subbrev_co_u32_e32 v6, vcc, 0, v6, vcc
	v_sub_u32_e32 v7, 0, v6
	v_ldexp_f32 v10, v10, v7
	v_ldexp_f32 v7, v11, v7
	v_add_f32_e32 v11, -1.0, v10
	v_add_f32_e32 v12, 1.0, v11
	v_sub_f32_e32 v12, v10, v12
	v_add_f32_e32 v12, v7, v12
	v_add_f32_e32 v13, v11, v12
	v_sub_f32_e32 v11, v11, v13
	v_add_f32_e32 v11, v12, v11
	v_add_f32_e32 v12, 1.0, v10
	v_add_f32_e32 v14, -1.0, v12
	v_sub_f32_e32 v10, v10, v14
	v_add_f32_e32 v7, v7, v10
	v_add_f32_e32 v10, v12, v7
	v_sub_f32_e32 v12, v12, v10
	v_add_f32_e32 v7, v7, v12
	v_rcp_f32_e32 v12, v10
	v_cvt_f32_i32_e32 v6, v6
	v_cmp_neq_f32_e32 vcc, s33, v9
	v_mul_f32_e32 v14, v13, v12
	v_mul_f32_e32 v15, v10, v14
	v_fma_f32 v16, v14, v10, -v15
	v_fmac_f32_e32 v16, v14, v7
	v_add_f32_e32 v17, v15, v16
	v_sub_f32_e32 v18, v13, v17
	v_sub_f32_e32 v13, v13, v18
	v_sub_f32_e32 v15, v17, v15
	v_sub_f32_e32 v13, v13, v17
	v_add_f32_e32 v11, v11, v13
	v_sub_f32_e32 v13, v15, v16
	v_add_f32_e32 v11, v13, v11
	v_add_f32_e32 v13, v18, v11
	v_mul_f32_e32 v15, v12, v13
	v_mul_f32_e32 v16, v10, v15
	v_fma_f32 v10, v15, v10, -v16
	v_fmac_f32_e32 v10, v15, v7
	v_sub_f32_e32 v7, v18, v13
	v_add_f32_e32 v7, v11, v7
	v_add_f32_e32 v11, v16, v10
	v_sub_f32_e32 v17, v13, v11
	v_sub_f32_e32 v13, v13, v17
	v_sub_f32_e32 v16, v11, v16
	v_sub_f32_e32 v11, v13, v11
	v_add_f32_e32 v7, v7, v11
	v_sub_f32_e32 v10, v16, v10
	v_add_f32_e32 v7, v10, v7
	v_add_f32_e32 v10, v14, v15
	v_add_f32_e32 v7, v17, v7
	v_sub_f32_e32 v11, v10, v14
	v_mul_f32_e32 v7, v12, v7
	v_sub_f32_e32 v11, v15, v11
	v_add_f32_e32 v7, v11, v7
	v_mul_f32_e32 v14, 0x3f317218, v6
	v_add_f32_e32 v11, v10, v7
	v_fma_f32 v15, v6, s26, -v14
	v_mul_f32_e32 v12, v11, v11
	v_fmac_f32_e32 v15, 0xb102e308, v6
	v_sub_f32_e32 v6, v11, v10
	v_fmamk_f32 v13, v12, 0x3e9b6dac, v238
	v_sub_f32_e32 v6, v7, v6
	v_add_f32_e32 v7, v14, v15
	v_fmaak_f32 v13, v12, v13, 0x3f2aaada
	v_sub_f32_e32 v10, v7, v14
	v_ldexp_f32 v14, v11, 1
	v_mul_f32_e32 v11, v11, v12
	v_mul_f32_e32 v11, v11, v13
	v_add_f32_e32 v12, v14, v11
	v_sub_f32_e32 v13, v12, v14
	v_ldexp_f32 v6, v6, 1
	v_sub_f32_e32 v11, v11, v13
	v_add_f32_e32 v6, v6, v11
	v_add_f32_e32 v11, v12, v6
	v_sub_f32_e32 v12, v11, v12
	v_sub_f32_e32 v6, v6, v12
	v_add_f32_e32 v12, v7, v11
	v_sub_f32_e32 v13, v12, v7
	v_sub_f32_e32 v14, v12, v13
	v_sub_f32_e32 v10, v15, v10
	v_sub_f32_e32 v7, v7, v14
	v_sub_f32_e32 v11, v11, v13
	v_add_f32_e32 v7, v11, v7
	v_add_f32_e32 v11, v10, v6
	v_sub_f32_e32 v13, v11, v10
	v_sub_f32_e32 v14, v11, v13
	v_sub_f32_e32 v10, v10, v14
	v_sub_f32_e32 v6, v6, v13
	v_add_f32_e32 v7, v11, v7
	v_add_f32_e32 v6, v6, v10
	v_add_f32_e32 v10, v12, v7
	v_sub_f32_e32 v11, v10, v12
	v_sub_f32_e32 v7, v7, v11
	v_add_f32_e32 v6, v6, v7
	v_add_f32_e32 v6, v10, v6
	v_cndmask_b32_e32 v6, v249, v6, vcc
	v_cmp_lt_f32_e64 vcc, |v9|, s27
	s_nop 1
	v_cndmask_b32_e32 v6, v6, v9, vcc
	v_add_f32_e32 v6, v8, v6
	v_mov_b32_e32 v8, v246
	v_mul_f32_e64 v7, v6, -v5
	v_mov_b32_e32 v0, v247
	s_waitcnt vmcnt(1)
	v_mul_f32_e32 v9, 0xbfb8aa3b, v8
	v_fma_f32 v10, v8, s6, -v9
	v_rndne_f32_e32 v11, v9
	v_fmac_f32_e32 v10, 0xb2a5705f, v8
	v_sub_f32_e32 v9, v9, v11
	v_add_f32_e32 v9, v9, v10
	v_exp_f32_e32 v9, v9
	v_cvt_i32_f32_e32 v10, v11
	v_cmp_nlt_f32_e32 vcc, s11, v8
	s_waitcnt vmcnt(0)
	v_mul_f32_e32 v1, 0xbfb8aa3b, v0
	v_ldexp_f32 v9, v9, v10
	v_cndmask_b32_e32 v9, 0, v9, vcc
	v_cmp_ngt_f32_e32 vcc, s16, v8
	v_rndne_f32_e32 v10, v1
	s_nop 0
	v_cndmask_b32_e32 v8, v249, v9, vcc
	v_fma_f32 v9, v0, s6, -v1
	v_fmac_f32_e32 v9, 0xb2a5705f, v0
	v_sub_f32_e32 v1, v1, v10
	v_add_f32_e32 v1, v1, v9
	v_exp_f32_e32 v1, v1
	v_cvt_i32_f32_e32 v9, v10
	v_cmp_nlt_f32_e32 vcc, s11, v0
	v_add_f32_e32 v8, 1.0, v8
	s_mov_b32 s6, 0x3fb8aa3b
	v_ldexp_f32 v1, v1, v9
	v_cndmask_b32_e32 v1, 0, v1, vcc
	v_cmp_ngt_f32_e32 vcc, s16, v0
	v_add_u32_e32 v9, 4, v124
	s_nop 0
	v_cndmask_b32_e32 v0, v249, v1, vcc
	v_cmp_ne_u32_e32 vcc, 0, v214
	v_add_f32_e32 v0, 1.0, v0
	s_nop 0
	v_subbrev_co_u32_e64 v1, s[40:41], 0, v214, vcc
	v_cmp_eq_u32_e64 s[40:41], 63, v214
	v_lshlrev_b32_e32 v1, 2, v1
	ds_bpermute_b32 v1, v1, v4
	v_cndmask_b32_e64 v9, v9, v242, s[40:41]
	ds_bpermute_b32 v9, v9, v7
	s_waitcnt lgkmcnt(1)
	v_fma_f32 v1, v3, -v2, v1
	v_cndmask_b32_e32 v1, v4, v1, vcc
	s_waitcnt lgkmcnt(0)
	v_fma_f32 v2, v6, -v5, v9
	v_cndmask_b32_e64 v2, v2, v7, s[40:41]
	v_cmp_gt_u32_e64 s[40:41], 2, v214
	v_cmp_gt_u32_e32 vcc, 62, v214
	v_add_u32_e32 v4, 8, v124
	v_cndmask_b32_e64 v3, -2, 0, s[40:41]
	v_add_lshl_u32 v3, v3, v214, 2
	ds_bpermute_b32 v3, v3, v1
	v_cndmask_b32_e32 v4, v124, v4, vcc
	ds_bpermute_b32 v4, v4, v2
	s_waitcnt lgkmcnt(1)
	v_add_f32_e32 v3, v1, v3
	v_cndmask_b32_e64 v1, v3, v1, s[40:41]
	s_waitcnt lgkmcnt(0)
	v_add_f32_e32 v3, v2, v4
	v_cndmask_b32_e32 v2, v2, v3, vcc
	v_cmp_gt_u32_e32 vcc, 4, v214
	v_add_u32_e32 v4, 16, v124
	v_cndmask_b32_e64 v4, v124, v4, s[42:43]
	v_cndmask_b32_e64 v3, -4, 0, vcc
	v_add_lshl_u32 v3, v3, v214, 2
	ds_bpermute_b32 v3, v3, v1
	ds_bpermute_b32 v4, v4, v2
	s_waitcnt lgkmcnt(1)
	v_add_f32_e32 v3, v1, v3
	v_cndmask_b32_e32 v1, v3, v1, vcc
	s_waitcnt lgkmcnt(0)
	v_add_f32_e32 v3, v2, v4
	v_cmp_gt_u32_e32 vcc, 8, v214
	v_cndmask_b32_e64 v2, v2, v3, s[42:43]
	v_cmp_gt_u32_e64 s[42:43], 56, v214
	v_cndmask_b32_e64 v3, -8, 0, vcc
	v_add_lshl_u32 v3, v3, v214, 2
	v_add_u32_e32 v4, 32, v124
	ds_bpermute_b32 v3, v3, v1
	v_cndmask_b32_e64 v4, v124, v4, s[42:43]
	ds_bpermute_b32 v4, v4, v2
	s_waitcnt lgkmcnt(1)
	v_add_f32_e32 v3, v1, v3
	v_cndmask_b32_e32 v1, v3, v1, vcc
	s_waitcnt lgkmcnt(0)
	v_add_f32_e32 v3, v2, v4
	v_cmp_gt_u32_e32 vcc, 16, v214
	v_cndmask_b32_e64 v2, v2, v3, s[42:43]
	v_cmp_gt_u32_e64 s[42:43], 48, v214
	v_cndmask_b32_e64 v3, -16, 0, vcc
	v_add_lshl_u32 v3, v3, v214, 2
	v_add_u32_e32 v4, 64, v124
	ds_bpermute_b32 v3, v3, v1
	v_cndmask_b32_e64 v4, v124, v4, s[42:43]
	ds_bpermute_b32 v4, v4, v2
	s_waitcnt lgkmcnt(1)
	v_add_f32_e32 v3, v1, v3
	v_cndmask_b32_e32 v1, v3, v1, vcc
	s_waitcnt lgkmcnt(0)
	v_add_f32_e32 v3, v2, v4
	v_cndmask_b32_e64 v2, v2, v3, s[42:43]
	v_lshlrev_b32_e32 v3, 2, v216
	v_cmp_gt_u32_e32 vcc, 32, v214
	v_and_b32_e32 v3, 0x7c, v3
	v_add_u32_e32 v4, 0x80, v124
	ds_bpermute_b32 v3, v3, v1
	v_cndmask_b32_e32 v4, v124, v4, vcc
	ds_bpermute_b32 v4, v4, v2
	s_waitcnt lgkmcnt(1)
	v_add_f32_e32 v3, v1, v3
	v_cndmask_b32_e32 v1, v3, v1, vcc
	s_waitcnt lgkmcnt(0)
	v_add_f32_e32 v3, v2, v4
	v_cndmask_b32_e32 v2, v2, v3, vcc
	v_div_scale_f32 v3, s[0:1], v8, v8, 1.0
	v_rcp_f32_e32 v4, v3
	s_nop 0
	v_fma_f32 v5, -v3, v4, 1.0
	v_fmac_f32_e32 v4, v5, v4
	v_div_scale_f32 v5, vcc, 1.0, v8, 1.0
	v_mul_f32_e32 v6, v5, v4
	v_fma_f32 v7, -v3, v6, v5
	v_fmac_f32_e32 v6, v7, v4
	v_fma_f32 v3, -v3, v6, v5
	v_div_fmas_f32 v3, v3, v4, v6
	v_div_scale_f32 v4, s[0:1], v0, v0, 1.0
	v_rcp_f32_e32 v5, v4
	v_div_fixup_f32 v3, v3, v8, 1.0
	v_readlane_b32 s0, v1, 63
	v_readlane_b32 s1, v2, 0
	v_fma_f32 v6, -v4, v5, 1.0
	v_fmac_f32_e32 v5, v6, v5
	v_div_scale_f32 v6, vcc, 1.0, v0, 1.0
	v_mul_f32_e32 v7, v6, v5
	v_fma_f32 v8, -v4, v7, v6
	v_fmac_f32_e32 v7, v8, v5
	v_fma_f32 v4, -v4, v7, v6
	v_div_fmas_f32 v4, v4, v5, v7
	v_div_fixup_f32 v0, v4, v0, 1.0
	v_mul_f32_e32 v4, 0x3fb8aa3b, v1
	v_fma_f32 v5, v1, s7, -v4
	v_rndne_f32_e32 v6, v4
	v_fmac_f32_e32 v5, 0x32a5705f, v1
	v_sub_f32_e32 v4, v4, v6
	v_add_f32_e32 v4, v4, v5
	v_exp_f32_e32 v4, v4
	v_cvt_i32_f32_e32 v5, v6
	v_cmp_ngt_f32_e32 vcc, s8, v1
	v_ldexp_f32 v4, v4, v5
	v_mul_f32_e32 v5, 0x3fb8aa3b, v2
	v_fma_f32 v6, v2, s7, -v5
	v_rndne_f32_e32 v7, v5
	v_fmac_f32_e32 v6, 0x32a5705f, v2
	v_sub_f32_e32 v5, v5, v7
	v_add_f32_e32 v5, v5, v6
	v_exp_f32_e32 v5, v5
	v_cvt_i32_f32_e32 v6, v7
	v_cndmask_b32_e32 v4, 0, v4, vcc
	v_cmp_nlt_f32_e32 vcc, s9, v1
	v_ldexp_f32 v5, v5, v6
	v_lshl_add_u32 v6, v214, 2, s2
	ds_write_b32 v6, v1
	v_sub_f32_e32 v1, s0, v1
	v_mul_f32_e32 v7, 0x3fb8aa3b, v1
	v_fma_f32 v8, v1, s7, -v7
	v_rndne_f32_e32 v9, v7
	v_fmac_f32_e32 v8, 0x32a5705f, v1
	v_sub_f32_e32 v7, v7, v9
	v_add_f32_e32 v7, v7, v8
	v_exp_f32_e32 v7, v7
	v_cvt_i32_f32_e32 v8, v9
	v_cndmask_b32_e32 v4, v249, v4, vcc
	v_cmp_ngt_f32_e32 vcc, s8, v2
	v_lshl_add_u32 v6, v186, 2, s2
	v_ldexp_f32 v7, v7, v8
	v_cndmask_b32_e32 v5, 0, v5, vcc
	v_cmp_nlt_f32_e32 vcc, s9, v2
	ds_write2st64_b32 v6, v2, v3 offset0:1 offset1:2
	ds_write2st64_b32 v6, v0, v4 offset0:3 offset1:4
	v_cndmask_b32_e32 v5, v249, v5, vcc
	v_cmp_ngt_f32_e32 vcc, s8, v1
	v_mul_f32_e32 v0, v0, v5
	ds_write_b32 v6, v0 offset:2304
	v_cndmask_b32_e32 v7, 0, v7, vcc
	v_cmp_nlt_f32_e32 vcc, s9, v1
	s_nop 1
	v_cndmask_b32_e32 v1, v249, v7, vcc
	ds_write2st64_b32 v6, v5, v1 offset0:5 offset1:6
	v_sub_f32_e32 v1, s1, v2
	v_mul_f32_e32 v2, 0x3fb8aa3b, v1
	v_fma_f32 v7, v1, s7, -v2
	v_rndne_f32_e32 v8, v2
	v_fmac_f32_e32 v7, 0x32a5705f, v1
	v_sub_f32_e32 v2, v2, v8
	v_add_f32_e32 v2, v2, v7
	v_exp_f32_e32 v2, v2
	v_cvt_i32_f32_e32 v7, v8
	v_cmp_ngt_f32_e32 vcc, s8, v1
	s_mov_b32 s7, 0xc2ce8ed0
	s_mov_b32 s8, 0x42b17218
	v_ldexp_f32 v2, v2, v7
	v_cndmask_b32_e32 v2, 0, v2, vcc
	v_cmp_nlt_f32_e32 vcc, s9, v1
	s_nop 1
	v_cndmask_b32_e32 v1, v249, v2, vcc
	v_mul_f32_e32 v2, v3, v4
	ds_write2st64_b32 v6, v1, v2 offset0:7 offset1:8
	s_and_b64 exec, exec, s[40:41]
	s_cbranch_execz .LBB0_194
	v_mov_b32_e32 v0, s1
	v_mov_b32_e32 v1, s0
	v_cmp_eq_u32_e32 vcc, 0, v214
	s_ashr_i32 s29, s28, 31
	s_lshl_b64 s[0:1], s[28:29], 3
	v_cndmask_b32_e32 v0, v0, v1, vcc
	v_mul_f32_e32 v1, 0x3fb8aa3b, v0
	v_fma_f32 v2, v0, s6, -v1
	v_rndne_f32_e32 v3, v1
	v_fmac_f32_e32 v2, 0x32a5705f, v0
	v_sub_f32_e32 v1, v1, v3
	v_add_f32_e32 v1, v1, v2
	v_exp_f32_e32 v1, v1
	v_cvt_i32_f32_e32 v2, v3
	v_cmp_ngt_f32_e32 vcc, s7, v0
	v_readlane_b32 s2, v251, 29
	s_add_u32 s0, s2, s0
	v_ldexp_f32 v1, v1, v2
	v_cndmask_b32_e32 v1, 0, v1, vcc
	v_cmp_nlt_f32_e32 vcc, s8, v0
	v_readlane_b32 s2, v251, 30
	s_addc_u32 s1, s2, s1
	v_cndmask_b32_e32 v0, v249, v1, vcc
	global_store_dword v124, v0, s[0:1]
